# moba_pre k_mean column sums: 64 loads in two in-flight batches with counted waits instead of 48 dependent round trips (same add order)
# speedup vs baseline: 1.0043x; 1.0043x over previous
.LBB0_164:
	s_mov_b32 s0, 0x7601400
	s_mov_b32 s1, 0
	v_lshl_add_u64 v[16:17], v[14:15], 0, s[0:1]
	s_add_u32 s0, s0, 0x1e00
	global_load_ushort v108, v[16:17], off
	v_lshl_add_u64 v[18:19], v[14:15], 0, s[0:1]
	s_add_u32 s0, s0, 0x1e00
	global_load_ushort v109, v[18:19], off
	v_lshl_add_u64 v[16:17], v[14:15], 0, s[0:1]
	s_add_u32 s0, s0, 0x1e00
	global_load_ushort v110, v[16:17], off
	v_lshl_add_u64 v[18:19], v[14:15], 0, s[0:1]
	s_add_u32 s0, s0, 0x1e00
	global_load_ushort v111, v[18:19], off
	v_lshl_add_u64 v[16:17], v[14:15], 0, s[0:1]
	s_add_u32 s0, s0, 0x1e00
	global_load_ushort v112, v[16:17], off
	v_lshl_add_u64 v[18:19], v[14:15], 0, s[0:1]
	s_add_u32 s0, s0, 0x1e00
	global_load_ushort v113, v[18:19], off
	v_lshl_add_u64 v[16:17], v[14:15], 0, s[0:1]
	s_add_u32 s0, s0, 0x1e00
	global_load_ushort v114, v[16:17], off
	v_lshl_add_u64 v[18:19], v[14:15], 0, s[0:1]
	s_add_u32 s0, s0, 0x1e00
	global_load_ushort v115, v[18:19], off
	v_lshl_add_u64 v[16:17], v[14:15], 0, s[0:1]
	s_add_u32 s0, s0, 0x1e00
	global_load_ushort v116, v[16:17], off
	v_lshl_add_u64 v[18:19], v[14:15], 0, s[0:1]
	s_add_u32 s0, s0, 0x1e00
	global_load_ushort v117, v[18:19], off
	v_lshl_add_u64 v[16:17], v[14:15], 0, s[0:1]
	s_add_u32 s0, s0, 0x1e00
	global_load_ushort v118, v[16:17], off
	v_lshl_add_u64 v[18:19], v[14:15], 0, s[0:1]
	s_add_u32 s0, s0, 0x1e00
	global_load_ushort v119, v[18:19], off
	v_lshl_add_u64 v[16:17], v[14:15], 0, s[0:1]
	s_add_u32 s0, s0, 0x1e00
	global_load_ushort v120, v[16:17], off
	v_lshl_add_u64 v[18:19], v[14:15], 0, s[0:1]
	s_add_u32 s0, s0, 0x1e00
	global_load_ushort v121, v[18:19], off
	v_lshl_add_u64 v[16:17], v[14:15], 0, s[0:1]
	s_add_u32 s0, s0, 0x1e00
	global_load_ushort v122, v[16:17], off
	v_lshl_add_u64 v[18:19], v[14:15], 0, s[0:1]
	s_add_u32 s0, s0, 0x1e00
	global_load_ushort v123, v[18:19], off
	v_lshl_add_u64 v[16:17], v[14:15], 0, s[0:1]
	s_add_u32 s0, s0, 0x1e00
	global_load_ushort v124, v[16:17], off
	v_lshl_add_u64 v[18:19], v[14:15], 0, s[0:1]
	s_add_u32 s0, s0, 0x1e00
	global_load_ushort v125, v[18:19], off
	v_lshl_add_u64 v[16:17], v[14:15], 0, s[0:1]
	s_add_u32 s0, s0, 0x1e00
	global_load_ushort v126, v[16:17], off
	v_lshl_add_u64 v[18:19], v[14:15], 0, s[0:1]
	s_add_u32 s0, s0, 0x1e00
	global_load_ushort v127, v[18:19], off
	v_lshl_add_u64 v[16:17], v[14:15], 0, s[0:1]
	s_add_u32 s0, s0, 0x1e00
	global_load_ushort v128, v[16:17], off
	v_lshl_add_u64 v[18:19], v[14:15], 0, s[0:1]
	s_add_u32 s0, s0, 0x1e00
	global_load_ushort v129, v[18:19], off
	v_lshl_add_u64 v[16:17], v[14:15], 0, s[0:1]
	s_add_u32 s0, s0, 0x1e00
	global_load_ushort v130, v[16:17], off
	v_lshl_add_u64 v[18:19], v[14:15], 0, s[0:1]
	s_add_u32 s0, s0, 0x1e00
	global_load_ushort v131, v[18:19], off
	v_lshl_add_u64 v[16:17], v[14:15], 0, s[0:1]
	s_add_u32 s0, s0, 0x1e00
	global_load_ushort v132, v[16:17], off
	v_lshl_add_u64 v[18:19], v[14:15], 0, s[0:1]
	s_add_u32 s0, s0, 0x1e00
	global_load_ushort v133, v[18:19], off
	v_lshl_add_u64 v[16:17], v[14:15], 0, s[0:1]
	s_add_u32 s0, s0, 0x1e00
	global_load_ushort v134, v[16:17], off
	v_lshl_add_u64 v[18:19], v[14:15], 0, s[0:1]
	s_add_u32 s0, s0, 0x1e00
	global_load_ushort v135, v[18:19], off
	v_lshl_add_u64 v[16:17], v[14:15], 0, s[0:1]
	s_add_u32 s0, s0, 0x1e00
	global_load_ushort v136, v[16:17], off
	v_lshl_add_u64 v[18:19], v[14:15], 0, s[0:1]
	s_add_u32 s0, s0, 0x1e00
	global_load_ushort v137, v[18:19], off
	v_lshl_add_u64 v[16:17], v[14:15], 0, s[0:1]
	s_add_u32 s0, s0, 0x1e00
	global_load_ushort v138, v[16:17], off
	v_lshl_add_u64 v[18:19], v[14:15], 0, s[0:1]
	s_add_u32 s0, s0, 0x1e00
	global_load_ushort v139, v[18:19], off
	s_waitcnt vmcnt(31)
	v_lshlrev_b32_e32 v108, 16, v108
	v_add_f32_e32 v13, v13, v108
	s_waitcnt vmcnt(30)
	v_lshlrev_b32_e32 v109, 16, v109
	v_add_f32_e32 v13, v13, v109
	s_waitcnt vmcnt(29)
	v_lshlrev_b32_e32 v110, 16, v110
	v_add_f32_e32 v13, v13, v110
	s_waitcnt vmcnt(28)
	v_lshlrev_b32_e32 v111, 16, v111
	v_add_f32_e32 v13, v13, v111
	s_waitcnt vmcnt(27)
	v_lshlrev_b32_e32 v112, 16, v112
	v_add_f32_e32 v13, v13, v112
	s_waitcnt vmcnt(26)
	v_lshlrev_b32_e32 v113, 16, v113
	v_add_f32_e32 v13, v13, v113
	s_waitcnt vmcnt(25)
	v_lshlrev_b32_e32 v114, 16, v114
	v_add_f32_e32 v13, v13, v114
	s_waitcnt vmcnt(24)
	v_lshlrev_b32_e32 v115, 16, v115
	v_add_f32_e32 v13, v13, v115
	s_waitcnt vmcnt(23)
	v_lshlrev_b32_e32 v116, 16, v116
	v_add_f32_e32 v13, v13, v116
	s_waitcnt vmcnt(22)
	v_lshlrev_b32_e32 v117, 16, v117
	v_add_f32_e32 v13, v13, v117
	s_waitcnt vmcnt(21)
	v_lshlrev_b32_e32 v118, 16, v118
	v_add_f32_e32 v13, v13, v118
	s_waitcnt vmcnt(20)
	v_lshlrev_b32_e32 v119, 16, v119
	v_add_f32_e32 v13, v13, v119
	s_waitcnt vmcnt(19)
	v_lshlrev_b32_e32 v120, 16, v120
	v_add_f32_e32 v13, v13, v120
	s_waitcnt vmcnt(18)
	v_lshlrev_b32_e32 v121, 16, v121
	v_add_f32_e32 v13, v13, v121
	s_waitcnt vmcnt(17)
	v_lshlrev_b32_e32 v122, 16, v122
	v_add_f32_e32 v13, v13, v122
	s_waitcnt vmcnt(16)
	v_lshlrev_b32_e32 v123, 16, v123
	v_add_f32_e32 v13, v13, v123
	s_waitcnt vmcnt(15)
	v_lshlrev_b32_e32 v124, 16, v124
	v_add_f32_e32 v13, v13, v124
	s_waitcnt vmcnt(14)
	v_lshlrev_b32_e32 v125, 16, v125
	v_add_f32_e32 v13, v13, v125
	s_waitcnt vmcnt(13)
	v_lshlrev_b32_e32 v126, 16, v126
	v_add_f32_e32 v13, v13, v126
	s_waitcnt vmcnt(12)
	v_lshlrev_b32_e32 v127, 16, v127
	v_add_f32_e32 v13, v13, v127
	s_waitcnt vmcnt(11)
	v_lshlrev_b32_e32 v128, 16, v128
	v_add_f32_e32 v13, v13, v128
	s_waitcnt vmcnt(10)
	v_lshlrev_b32_e32 v129, 16, v129
	v_add_f32_e32 v13, v13, v129
	s_waitcnt vmcnt(9)
	v_lshlrev_b32_e32 v130, 16, v130
	v_add_f32_e32 v13, v13, v130
	s_waitcnt vmcnt(8)
	v_lshlrev_b32_e32 v131, 16, v131
	v_add_f32_e32 v13, v13, v131
	s_waitcnt vmcnt(7)
	v_lshlrev_b32_e32 v132, 16, v132
	v_add_f32_e32 v13, v13, v132
	s_waitcnt vmcnt(6)
	v_lshlrev_b32_e32 v133, 16, v133
	v_add_f32_e32 v13, v13, v133
	s_waitcnt vmcnt(5)
	v_lshlrev_b32_e32 v134, 16, v134
	v_add_f32_e32 v13, v13, v134
	s_waitcnt vmcnt(4)
	v_lshlrev_b32_e32 v135, 16, v135
	v_add_f32_e32 v13, v13, v135
	s_waitcnt vmcnt(3)
	v_lshlrev_b32_e32 v136, 16, v136
	v_add_f32_e32 v13, v13, v136
	s_waitcnt vmcnt(2)
	v_lshlrev_b32_e32 v137, 16, v137
	v_add_f32_e32 v13, v13, v137
	s_waitcnt vmcnt(1)
	v_lshlrev_b32_e32 v138, 16, v138
	v_add_f32_e32 v13, v13, v138
	s_waitcnt vmcnt(0)
	v_lshlrev_b32_e32 v139, 16, v139
	v_add_f32_e32 v13, v13, v139
	v_lshl_add_u64 v[16:17], v[14:15], 0, s[0:1]
	s_add_u32 s0, s0, 0x1e00
	global_load_ushort v108, v[16:17], off
	v_lshl_add_u64 v[18:19], v[14:15], 0, s[0:1]
	s_add_u32 s0, s0, 0x1e00
	global_load_ushort v109, v[18:19], off
	v_lshl_add_u64 v[16:17], v[14:15], 0, s[0:1]
	s_add_u32 s0, s0, 0x1e00
	global_load_ushort v110, v[16:17], off
	v_lshl_add_u64 v[18:19], v[14:15], 0, s[0:1]
	s_add_u32 s0, s0, 0x1e00
	global_load_ushort v111, v[18:19], off
	v_lshl_add_u64 v[16:17], v[14:15], 0, s[0:1]
	s_add_u32 s0, s0, 0x1e00
	global_load_ushort v112, v[16:17], off
	v_lshl_add_u64 v[18:19], v[14:15], 0, s[0:1]
	s_add_u32 s0, s0, 0x1e00
	global_load_ushort v113, v[18:19], off
	v_lshl_add_u64 v[16:17], v[14:15], 0, s[0:1]
	s_add_u32 s0, s0, 0x1e00
	global_load_ushort v114, v[16:17], off
	v_lshl_add_u64 v[18:19], v[14:15], 0, s[0:1]
	s_add_u32 s0, s0, 0x1e00
	global_load_ushort v115, v[18:19], off
	v_lshl_add_u64 v[16:17], v[14:15], 0, s[0:1]
	s_add_u32 s0, s0, 0x1e00
	global_load_ushort v116, v[16:17], off
	v_lshl_add_u64 v[18:19], v[14:15], 0, s[0:1]
	s_add_u32 s0, s0, 0x1e00
	global_load_ushort v117, v[18:19], off
	v_lshl_add_u64 v[16:17], v[14:15], 0, s[0:1]
	s_add_u32 s0, s0, 0x1e00
	global_load_ushort v118, v[16:17], off
	v_lshl_add_u64 v[18:19], v[14:15], 0, s[0:1]
	s_add_u32 s0, s0, 0x1e00
	global_load_ushort v119, v[18:19], off
	v_lshl_add_u64 v[16:17], v[14:15], 0, s[0:1]
	s_add_u32 s0, s0, 0x1e00
	global_load_ushort v120, v[16:17], off
	v_lshl_add_u64 v[18:19], v[14:15], 0, s[0:1]
	s_add_u32 s0, s0, 0x1e00
	global_load_ushort v121, v[18:19], off
	v_lshl_add_u64 v[16:17], v[14:15], 0, s[0:1]
	s_add_u32 s0, s0, 0x1e00
	global_load_ushort v122, v[16:17], off
	v_lshl_add_u64 v[18:19], v[14:15], 0, s[0:1]
	s_add_u32 s0, s0, 0x1e00
	global_load_ushort v123, v[18:19], off
	v_lshl_add_u64 v[16:17], v[14:15], 0, s[0:1]
	s_add_u32 s0, s0, 0x1e00
	global_load_ushort v124, v[16:17], off
	v_lshl_add_u64 v[18:19], v[14:15], 0, s[0:1]
	s_add_u32 s0, s0, 0x1e00
	global_load_ushort v125, v[18:19], off
	v_lshl_add_u64 v[16:17], v[14:15], 0, s[0:1]
	s_add_u32 s0, s0, 0x1e00
	global_load_ushort v126, v[16:17], off
	v_lshl_add_u64 v[18:19], v[14:15], 0, s[0:1]
	s_add_u32 s0, s0, 0x1e00
	global_load_ushort v127, v[18:19], off
	v_lshl_add_u64 v[16:17], v[14:15], 0, s[0:1]
	s_add_u32 s0, s0, 0x1e00
	global_load_ushort v128, v[16:17], off
	v_lshl_add_u64 v[18:19], v[14:15], 0, s[0:1]
	s_add_u32 s0, s0, 0x1e00
	global_load_ushort v129, v[18:19], off
	v_lshl_add_u64 v[16:17], v[14:15], 0, s[0:1]
	s_add_u32 s0, s0, 0x1e00
	global_load_ushort v130, v[16:17], off
	v_lshl_add_u64 v[18:19], v[14:15], 0, s[0:1]
	s_add_u32 s0, s0, 0x1e00
	global_load_ushort v131, v[18:19], off
	v_lshl_add_u64 v[16:17], v[14:15], 0, s[0:1]
	s_add_u32 s0, s0, 0x1e00
	global_load_ushort v132, v[16:17], off
	v_lshl_add_u64 v[18:19], v[14:15], 0, s[0:1]
	s_add_u32 s0, s0, 0x1e00
	global_load_ushort v133, v[18:19], off
	v_lshl_add_u64 v[16:17], v[14:15], 0, s[0:1]
	s_add_u32 s0, s0, 0x1e00
	global_load_ushort v134, v[16:17], off
	v_lshl_add_u64 v[18:19], v[14:15], 0, s[0:1]
	s_add_u32 s0, s0, 0x1e00
	global_load_ushort v135, v[18:19], off
	v_lshl_add_u64 v[16:17], v[14:15], 0, s[0:1]
	s_add_u32 s0, s0, 0x1e00
	global_load_ushort v136, v[16:17], off
	v_lshl_add_u64 v[18:19], v[14:15], 0, s[0:1]
	s_add_u32 s0, s0, 0x1e00
	global_load_ushort v137, v[18:19], off
	v_lshl_add_u64 v[16:17], v[14:15], 0, s[0:1]
	s_add_u32 s0, s0, 0x1e00
	global_load_ushort v138, v[16:17], off
	v_lshl_add_u64 v[18:19], v[14:15], 0, s[0:1]
	s_add_u32 s0, s0, 0x1e00
	global_load_ushort v139, v[18:19], off
	s_waitcnt vmcnt(31)
	v_lshlrev_b32_e32 v108, 16, v108
	v_add_f32_e32 v13, v13, v108
	s_waitcnt vmcnt(30)
	v_lshlrev_b32_e32 v109, 16, v109
	v_add_f32_e32 v13, v13, v109
	s_waitcnt vmcnt(29)
	v_lshlrev_b32_e32 v110, 16, v110
	v_add_f32_e32 v13, v13, v110
	s_waitcnt vmcnt(28)
	v_lshlrev_b32_e32 v111, 16, v111
	v_add_f32_e32 v13, v13, v111
	s_waitcnt vmcnt(27)
	v_lshlrev_b32_e32 v112, 16, v112
	v_add_f32_e32 v13, v13, v112
	s_waitcnt vmcnt(26)
	v_lshlrev_b32_e32 v113, 16, v113
	v_add_f32_e32 v13, v13, v113
	s_waitcnt vmcnt(25)
	v_lshlrev_b32_e32 v114, 16, v114
	v_add_f32_e32 v13, v13, v114
	s_waitcnt vmcnt(24)
	v_lshlrev_b32_e32 v115, 16, v115
	v_add_f32_e32 v13, v13, v115
	s_waitcnt vmcnt(23)
	v_lshlrev_b32_e32 v116, 16, v116
	v_add_f32_e32 v13, v13, v116
	s_waitcnt vmcnt(22)
	v_lshlrev_b32_e32 v117, 16, v117
	v_add_f32_e32 v13, v13, v117
	s_waitcnt vmcnt(21)
	v_lshlrev_b32_e32 v118, 16, v118
	v_add_f32_e32 v13, v13, v118
	s_waitcnt vmcnt(20)
	v_lshlrev_b32_e32 v119, 16, v119
	v_add_f32_e32 v13, v13, v119
	s_waitcnt vmcnt(19)
	v_lshlrev_b32_e32 v120, 16, v120
	v_add_f32_e32 v13, v13, v120
	s_waitcnt vmcnt(18)
	v_lshlrev_b32_e32 v121, 16, v121
	v_add_f32_e32 v13, v13, v121
	s_waitcnt vmcnt(17)
	v_lshlrev_b32_e32 v122, 16, v122
	v_add_f32_e32 v13, v13, v122
	s_waitcnt vmcnt(16)
	v_lshlrev_b32_e32 v123, 16, v123
	v_add_f32_e32 v13, v13, v123
	s_waitcnt vmcnt(15)
	v_lshlrev_b32_e32 v124, 16, v124
	v_add_f32_e32 v13, v13, v124
	s_waitcnt vmcnt(14)
	v_lshlrev_b32_e32 v125, 16, v125
	v_add_f32_e32 v13, v13, v125
	s_waitcnt vmcnt(13)
	v_lshlrev_b32_e32 v126, 16, v126
	v_add_f32_e32 v13, v13, v126
	s_waitcnt vmcnt(12)
	v_lshlrev_b32_e32 v127, 16, v127
	v_add_f32_e32 v13, v13, v127
	s_waitcnt vmcnt(11)
	v_lshlrev_b32_e32 v128, 16, v128
	v_add_f32_e32 v13, v13, v128
	s_waitcnt vmcnt(10)
	v_lshlrev_b32_e32 v129, 16, v129
	v_add_f32_e32 v13, v13, v129
	s_waitcnt vmcnt(9)
	v_lshlrev_b32_e32 v130, 16, v130
	v_add_f32_e32 v13, v13, v130
	s_waitcnt vmcnt(8)
	v_lshlrev_b32_e32 v131, 16, v131
	v_add_f32_e32 v13, v13, v131
	s_waitcnt vmcnt(7)
	v_lshlrev_b32_e32 v132, 16, v132
	v_add_f32_e32 v13, v13, v132
	s_waitcnt vmcnt(6)
	v_lshlrev_b32_e32 v133, 16, v133
	v_add_f32_e32 v13, v13, v133
	s_waitcnt vmcnt(5)
	v_lshlrev_b32_e32 v134, 16, v134
	v_add_f32_e32 v13, v13, v134
	s_waitcnt vmcnt(4)
	v_lshlrev_b32_e32 v135, 16, v135
	v_add_f32_e32 v13, v13, v135
	s_waitcnt vmcnt(3)
	v_lshlrev_b32_e32 v136, 16, v136
	v_add_f32_e32 v13, v13, v136
	s_waitcnt vmcnt(2)
	v_lshlrev_b32_e32 v137, 16, v137
	v_add_f32_e32 v13, v13, v137
	s_waitcnt vmcnt(1)
	v_lshlrev_b32_e32 v138, 16, v138
	v_add_f32_e32 v13, v13, v138
	s_waitcnt vmcnt(0)
	v_lshlrev_b32_e32 v139, 16, v139
	v_add_f32_e32 v13, v13, v139
	ds_write_b32 v59, v13
	s_waitcnt lgkmcnt(0)
	s_barrier
	s_and_saveexec_b64 s[0:1], s[6:7]
	s_cbranch_execz .LBB0_167
	ds_read2st64_b32 v[14:15], v59 offset1:2
	ds_read2st64_b32 v[16:17], v59 offset0:4 offset1:6
	s_and_b32 s17, s10, 0xffffff80
	s_lshl_b32 s15, s15, 5
	s_or_b32 s15, s15, s17
	s_waitcnt lgkmcnt(1)
	v_mov_b32_e32 v18, v14
	s_waitcnt lgkmcnt(0)
	v_mov_b32_e32 v19, v16
	v_mov_b32_e32 v16, v15
	s_or_b32 s14, s15, s14
	v_pk_add_f32 v[14:15], v[18:19], v[16:17]
	s_ashr_i32 s15, s14, 31
	v_add_f32_e32 v13, v14, v15
	s_lshl_b64 s[14:15], s[14:15], 9
	v_mul_f32_e32 v13, 0x3b800000, v13
	v_lshl_add_u64 v[14:15], v[4:5], 0, s[14:15]
	global_store_dword v[14:15], v13, off
